# grid barrier release: non-leader WGs poll the top-level generation word directly (one hop less); per-XCD release atomic dropped
# speedup vs baseline: 1.0107x; 1.0091x over previous
; __device__ __forceinline__ unsigned xb_ld(unsigned* p)              { return __hip_atomic_load(p, __ATOMIC_RELAXED, __HIP_MEMORY_SCOPE_AGENT); }
; __device__ __forceinline__ unsigned xb_add(unsigned* p, unsigned v) { return __hip_atomic_fetch_add(p, v, __ATOMIC_RELAXED, __HIP_MEMORY_SCOPE_AGENT); }
; #define XB_SPIN(cond, bar) do { unsigned _sp = 0; while (cond) { __builtin_amdgcn_s_sleep(1); \
;     if ((++_sp & 255u) == 0u) { if (xb_ld(&(bar)[XB_TMO])) break; if (_sp > XB_SPIN_CAP) { atomicAdd(&(bar)[XB_TMO], 1u); break; } } } } while (0)
; __device__ __forceinline__ void xcd_barrier(const XcdBarrier& b) {
;     ...
;         const unsigned old = xb_add(&bar[XB_XSUB(b.x)], 1u);
;         const unsigned gen = old / nloc;
;         if (old + 1u == (gen + 1u) * nloc) {
;             __builtin_amdgcn_fence(__ATOMIC_RELEASE, "agent");
;             asm volatile("s_waitcnt vmcnt(0)" ::: "memory");
;             const unsigned og = xb_add(&bar[XB_TOP], 1u);
;             const unsigned tg = og / nx;
;             if (og + 1u == (tg + 1u) * nx) xb_add(&bar[XB_TOPGEN], 1u);
;             else XB_SPIN(xb_ld(&bar[XB_TOPGEN]) == tg, bar);
;             __builtin_amdgcn_fence(__ATOMIC_ACQUIRE, "agent");
;             xb_add(&bar[XB_XGEN(b.x)], 1u);
;             asm volatile("s_waitcnt vmcnt(0)" ::: "memory");
;         } else {
;             XB_SPIN(xb_ld(&bar[XB_XGEN(b.x)]) == gen, bar);
;             __builtin_amdgcn_fence(__ATOMIC_ACQUIRE, "agent");
;             asm volatile("s_waitcnt vmcnt(0)" ::: "memory");
.LBB0_144:
	s_or_b64 exec, exec, s[8:9]
	v_cvt_f32_u32_e32 v5, v3
	s_waitcnt vmcnt(0)
	v_readfirstlane_b32 s3, v4
	v_sub_u32_e32 v4, 0, v3
	v_rcp_iflag_f32_e32 v5, v5
	v_add_u32_e32 v6, s3, v2
	v_mul_f32_e32 v5, 0x4f7ffffe, v5
	v_cvt_u32_f32_e32 v5, v5
	v_mul_lo_u32 v2, v4, v5
	v_mul_hi_u32 v2, v5, v2
	v_add_u32_e32 v2, v5, v2
	v_mul_hi_u32 v2, v6, v2
	v_mul_lo_u32 v4, v2, v3
	v_sub_u32_e32 v4, v6, v4
	v_add_u32_e32 v5, 1, v2
	v_cmp_ge_u32_e32 vcc, v4, v3
	s_nop 1
	v_cndmask_b32_e32 v2, v2, v5, vcc
	v_sub_u32_e32 v5, v4, v3
	v_cndmask_b32_e32 v4, v4, v5, vcc
	v_add_u32_e32 v5, 1, v2
	v_cmp_ge_u32_e32 vcc, v4, v3
	v_add_u32_e32 v4, 1, v6
	s_nop 0
	v_cndmask_b32_e32 v2, v2, v5, vcc
	v_mul_lo_u32 v5, v3, v2
	v_add_u32_e32 v3, v5, v3
	v_cmp_ne_u32_e32 vcc, v4, v3
	s_and_saveexec_b64 s[6:7], vcc
	s_xor_b64 s[6:7], exec, s[6:7]
	s_cbranch_execz .LBB0_158
	s_waitcnt lgkmcnt(0)
	v_mov_b32_e32 v1, 0x3500
	global_load_dword v1, v1, s[30:31] sc1
	s_add_u32 s10, s30, 0x3500
	s_addc_u32 s11, s31, 0
	s_waitcnt vmcnt(0)
	v_cmp_eq_u32_e32 vcc, v1, v2
	s_and_saveexec_b64 s[8:9], vcc
	s_cbranch_execz .LBB0_157
	s_mov_b32 s3, 1
	s_mov_b64 s[12:13], 0
	v_mov_b32_e32 v1, 0
	s_branch .LBB0_148

; __device__ __forceinline__ unsigned xb_ld(unsigned* p)              { return __hip_atomic_load(p, __ATOMIC_RELAXED, __HIP_MEMORY_SCOPE_AGENT); }
; __device__ __forceinline__ unsigned xb_add(unsigned* p, unsigned v) { return __hip_atomic_fetch_add(p, v, __ATOMIC_RELAXED, __HIP_MEMORY_SCOPE_AGENT); }
; #define XB_SPIN(cond, bar) do { unsigned _sp = 0; while (cond) { __builtin_amdgcn_s_sleep(1); \
;     if ((++_sp & 255u) == 0u) { if (xb_ld(&(bar)[XB_TMO])) break; if (_sp > XB_SPIN_CAP) { atomicAdd(&(bar)[XB_TMO], 1u); break; } } } } while (0)
; __device__ __forceinline__ void xcd_barrier(const XcdBarrier& b) {
;     ...
;             const unsigned tg = og / nx;
;             if (og + 1u == (tg + 1u) * nx) xb_add(&bar[XB_TOPGEN], 1u);
;             else XB_SPIN(xb_ld(&bar[XB_TOPGEN]) == tg, bar);
;             __builtin_amdgcn_fence(__ATOMIC_ACQUIRE, "agent");
;             xb_add(&bar[XB_XGEN(b.x)], 1u);
;             asm volatile("s_waitcnt vmcnt(0)" ::: "memory");
.LBB0_175:
	s_or_b64 exec, exec, s[8:9]
	s_mov_b64 s[8:9], exec
	v_mbcnt_lo_u32_b32 v1, s8, 0
	v_mbcnt_hi_u32_b32 v1, s9, v1
	v_cmp_eq_u32_e32 vcc, 0, v1
	s_waitcnt vmcnt(0)
	buffer_inv sc1
	s_and_saveexec_b64 s[10:11], vcc
	s_cbranch_execz .LBB0_177
	s_bcnt1_i32_b64 s3, s[8:9]
	v_mov_b32_e32 v1, 0x2000
	v_mov_b32_e32 v2, s3
.LBB0_177:
	s_or_b64 exec, exec, s[10:11]
	s_waitcnt vmcnt(0)

; __device__ __forceinline__ unsigned xb_ld(unsigned* p)              { return __hip_atomic_load(p, __ATOMIC_RELAXED, __HIP_MEMORY_SCOPE_AGENT); }
; __device__ __forceinline__ unsigned xb_add(unsigned* p, unsigned v) { return __hip_atomic_fetch_add(p, v, __ATOMIC_RELAXED, __HIP_MEMORY_SCOPE_AGENT); }
; #define XB_SPIN(cond, bar) do { unsigned _sp = 0; while (cond) { __builtin_amdgcn_s_sleep(1); \
;     if ((++_sp & 255u) == 0u) { if (xb_ld(&(bar)[XB_TMO])) break; if (_sp > XB_SPIN_CAP) { atomicAdd(&(bar)[XB_TMO], 1u); break; } } } } while (0)
; __device__ __forceinline__ void xcd_barrier(const XcdBarrier& b) {
;     ...
;         const unsigned old = xb_add(&bar[XB_XSUB(b.x)], 1u);
;         const unsigned gen = old / nloc;
;         if (old + 1u == (gen + 1u) * nloc) {
;             __builtin_amdgcn_fence(__ATOMIC_RELEASE, "agent");
;             asm volatile("s_waitcnt vmcnt(0)" ::: "memory");
;             const unsigned og = xb_add(&bar[XB_TOP], 1u);
;             const unsigned tg = og / nx;
;             if (og + 1u == (tg + 1u) * nx) xb_add(&bar[XB_TOPGEN], 1u);
;             else XB_SPIN(xb_ld(&bar[XB_TOPGEN]) == tg, bar);
;             __builtin_amdgcn_fence(__ATOMIC_ACQUIRE, "agent");
;             xb_add(&bar[XB_XGEN(b.x)], 1u);
;             asm volatile("s_waitcnt vmcnt(0)" ::: "memory");
;         } else {
;             XB_SPIN(xb_ld(&bar[XB_XGEN(b.x)]) == gen, bar);
;             __builtin_amdgcn_fence(__ATOMIC_ACQUIRE, "agent");
;             asm volatile("s_waitcnt vmcnt(0)" ::: "memory");
.LBB0_247:
	s_or_b64 exec, exec, s[8:9]
	v_cvt_f32_u32_e32 v5, v3
	s_waitcnt vmcnt(0)
	v_readfirstlane_b32 s6, v4
	v_sub_u32_e32 v4, 0, v3
	v_rcp_iflag_f32_e32 v5, v5
	v_add_u32_e32 v6, s6, v2
	v_mul_f32_e32 v5, 0x4f7ffffe, v5
	v_cvt_u32_f32_e32 v5, v5
	v_mul_lo_u32 v2, v4, v5
	v_mul_hi_u32 v2, v5, v2
	v_add_u32_e32 v2, v5, v2
	v_mul_hi_u32 v2, v6, v2
	v_mul_lo_u32 v4, v2, v3
	v_sub_u32_e32 v4, v6, v4
	v_add_u32_e32 v5, 1, v2
	v_cmp_ge_u32_e32 vcc, v4, v3
	s_nop 1
	v_cndmask_b32_e32 v2, v2, v5, vcc
	v_sub_u32_e32 v5, v4, v3
	v_cndmask_b32_e32 v4, v4, v5, vcc
	v_add_u32_e32 v5, 1, v2
	v_cmp_ge_u32_e32 vcc, v4, v3
	v_add_u32_e32 v4, 1, v6
	s_nop 0
	v_cndmask_b32_e32 v2, v2, v5, vcc
	v_mul_lo_u32 v5, v3, v2
	v_add_u32_e32 v3, v5, v3
	v_cmp_ne_u32_e32 vcc, v4, v3
	s_and_saveexec_b64 s[6:7], vcc
	s_xor_b64 s[6:7], exec, s[6:7]
	s_cbranch_execz .LBB0_261
	s_waitcnt lgkmcnt(0)
	v_mov_b32_e32 v1, 0x3500
	global_load_dword v1, v1, s[30:31] sc1
	s_add_u32 s10, s30, 0x3500
	s_addc_u32 s11, s31, 0
	s_waitcnt vmcnt(0)
	v_cmp_eq_u32_e32 vcc, v1, v2
	s_and_saveexec_b64 s[8:9], vcc
	s_cbranch_execz .LBB0_260
	s_mov_b32 s33, 1
	s_mov_b64 s[12:13], 0
	v_mov_b32_e32 v1, 0
	s_branch .LBB0_251

; __device__ __forceinline__ unsigned xb_ld(unsigned* p)              { return __hip_atomic_load(p, __ATOMIC_RELAXED, __HIP_MEMORY_SCOPE_AGENT); }
; __device__ __forceinline__ unsigned xb_add(unsigned* p, unsigned v) { return __hip_atomic_fetch_add(p, v, __ATOMIC_RELAXED, __HIP_MEMORY_SCOPE_AGENT); }
; #define XB_SPIN(cond, bar) do { unsigned _sp = 0; while (cond) { __builtin_amdgcn_s_sleep(1); \
;     if ((++_sp & 255u) == 0u) { if (xb_ld(&(bar)[XB_TMO])) break; if (_sp > XB_SPIN_CAP) { atomicAdd(&(bar)[XB_TMO], 1u); break; } } } } while (0)
; __device__ __forceinline__ void xcd_barrier(const XcdBarrier& b) {
;     ...
;             const unsigned tg = og / nx;
;             if (og + 1u == (tg + 1u) * nx) xb_add(&bar[XB_TOPGEN], 1u);
;             else XB_SPIN(xb_ld(&bar[XB_TOPGEN]) == tg, bar);
;             __builtin_amdgcn_fence(__ATOMIC_ACQUIRE, "agent");
;             xb_add(&bar[XB_XGEN(b.x)], 1u);
;             asm volatile("s_waitcnt vmcnt(0)" ::: "memory");
.LBB0_278:
	s_or_b64 exec, exec, s[8:9]
	s_mov_b64 s[8:9], exec
	v_mbcnt_lo_u32_b32 v1, s8, 0
	v_mbcnt_hi_u32_b32 v1, s9, v1
	v_cmp_eq_u32_e32 vcc, 0, v1
	s_waitcnt vmcnt(0)
	buffer_inv sc1
	s_and_saveexec_b64 s[10:11], vcc
	s_cbranch_execz .LBB0_280
	s_bcnt1_i32_b64 s8, s[8:9]
	v_mov_b32_e32 v1, 0x2000
	v_mov_b32_e32 v2, s8
.LBB0_280:
	s_or_b64 exec, exec, s[10:11]
	s_waitcnt vmcnt(0)

; __device__ __forceinline__ unsigned xb_ld(unsigned* p)              { return __hip_atomic_load(p, __ATOMIC_RELAXED, __HIP_MEMORY_SCOPE_AGENT); }
; __device__ __forceinline__ unsigned xb_add(unsigned* p, unsigned v) { return __hip_atomic_fetch_add(p, v, __ATOMIC_RELAXED, __HIP_MEMORY_SCOPE_AGENT); }
; #define XB_SPIN(cond, bar) do { unsigned _sp = 0; while (cond) { __builtin_amdgcn_s_sleep(1); \
;     if ((++_sp & 255u) == 0u) { if (xb_ld(&(bar)[XB_TMO])) break; if (_sp > XB_SPIN_CAP) { atomicAdd(&(bar)[XB_TMO], 1u); break; } } } } while (0)
; __device__ __forceinline__ void xcd_barrier(const XcdBarrier& b) {
;     ...
;             const unsigned tg = og / nx;
;             if (og + 1u == (tg + 1u) * nx) xb_add(&bar[XB_TOPGEN], 1u);
;             else XB_SPIN(xb_ld(&bar[XB_TOPGEN]) == tg, bar);
;             __builtin_amdgcn_fence(__ATOMIC_ACQUIRE, "agent");
;             xb_add(&bar[XB_XGEN(b.x)], 1u);
;             asm volatile("s_waitcnt vmcnt(0)" ::: "memory");
.LBB0_427:
	s_or_b64 exec, exec, s[8:9]
	s_mov_b64 s[8:9], exec
	v_mbcnt_lo_u32_b32 v1, s8, 0
	v_mbcnt_hi_u32_b32 v1, s9, v1
	v_cmp_eq_u32_e32 vcc, 0, v1
	s_waitcnt vmcnt(0)
	buffer_inv sc1
	s_and_saveexec_b64 s[10:11], vcc
	s_cbranch_execz .LBB0_429
	s_bcnt1_i32_b64 s8, s[8:9]
	v_mov_b32_e32 v1, 0x2000
	v_mov_b32_e32 v2, s8
.LBB0_429:
	s_or_b64 exec, exec, s[10:11]
	s_waitcnt vmcnt(0)

; __device__ __forceinline__ unsigned xb_ld(unsigned* p)              { return __hip_atomic_load(p, __ATOMIC_RELAXED, __HIP_MEMORY_SCOPE_AGENT); }
; __device__ __forceinline__ unsigned xb_add(unsigned* p, unsigned v) { return __hip_atomic_fetch_add(p, v, __ATOMIC_RELAXED, __HIP_MEMORY_SCOPE_AGENT); }
; #define XB_SPIN(cond, bar) do { unsigned _sp = 0; while (cond) { __builtin_amdgcn_s_sleep(1); \
;     if ((++_sp & 255u) == 0u) { if (xb_ld(&(bar)[XB_TMO])) break; if (_sp > XB_SPIN_CAP) { atomicAdd(&(bar)[XB_TMO], 1u); break; } } } } while (0)
; __device__ __forceinline__ void xcd_barrier(const XcdBarrier& b) {
;     ...
;         const unsigned old = xb_add(&bar[XB_XSUB(b.x)], 1u);
;         const unsigned gen = old / nloc;
;         if (old + 1u == (gen + 1u) * nloc) {
;             __builtin_amdgcn_fence(__ATOMIC_RELEASE, "agent");
;             asm volatile("s_waitcnt vmcnt(0)" ::: "memory");
;             const unsigned og = xb_add(&bar[XB_TOP], 1u);
;             const unsigned tg = og / nx;
;             if (og + 1u == (tg + 1u) * nx) xb_add(&bar[XB_TOPGEN], 1u);
;             else XB_SPIN(xb_ld(&bar[XB_TOPGEN]) == tg, bar);
;             __builtin_amdgcn_fence(__ATOMIC_ACQUIRE, "agent");
;             xb_add(&bar[XB_XGEN(b.x)], 1u);
;             asm volatile("s_waitcnt vmcnt(0)" ::: "memory");
;         } else {
;             XB_SPIN(xb_ld(&bar[XB_XGEN(b.x)]) == gen, bar);
;             __builtin_amdgcn_fence(__ATOMIC_ACQUIRE, "agent");
;             asm volatile("s_waitcnt vmcnt(0)" ::: "memory");
.LBB0_737:
	s_or_b64 exec, exec, s[8:9]
	v_cvt_f32_u32_e32 v5, v3
	s_waitcnt vmcnt(0)
	v_readfirstlane_b32 s6, v4
	v_sub_u32_e32 v4, 0, v3
	v_rcp_iflag_f32_e32 v5, v5
	v_add_u32_e32 v6, s6, v2
	v_mul_f32_e32 v5, 0x4f7ffffe, v5
	v_cvt_u32_f32_e32 v5, v5
	v_mul_lo_u32 v2, v4, v5
	v_mul_hi_u32 v2, v5, v2
	v_add_u32_e32 v2, v5, v2
	v_mul_hi_u32 v2, v6, v2
	v_mul_lo_u32 v4, v2, v3
	v_sub_u32_e32 v4, v6, v4
	v_add_u32_e32 v5, 1, v2
	v_cmp_ge_u32_e32 vcc, v4, v3
	s_nop 1
	v_cndmask_b32_e32 v2, v2, v5, vcc
	v_sub_u32_e32 v5, v4, v3
	v_cndmask_b32_e32 v4, v4, v5, vcc
	v_add_u32_e32 v5, 1, v2
	v_cmp_ge_u32_e32 vcc, v4, v3
	v_add_u32_e32 v4, 1, v6
	s_nop 0
	v_cndmask_b32_e32 v2, v2, v5, vcc
	v_mul_lo_u32 v5, v3, v2
	v_add_u32_e32 v3, v5, v3
	v_cmp_ne_u32_e32 vcc, v4, v3
	s_and_saveexec_b64 s[6:7], vcc
	s_xor_b64 s[6:7], exec, s[6:7]
	s_cbranch_execz .LBB0_751
	s_waitcnt lgkmcnt(0)
	v_mov_b32_e32 v1, 0x3500
	global_load_dword v1, v1, s[30:31] sc1
	s_add_u32 s12, s30, 0x3500
	s_addc_u32 s13, s31, 0
	s_waitcnt vmcnt(0)
	v_cmp_eq_u32_e32 vcc, v1, v2
	s_and_saveexec_b64 s[8:9], vcc
	s_cbranch_execz .LBB0_750
	s_mov_b32 s33, 1
	s_mov_b64 s[14:15], 0
	v_mov_b32_e32 v1, 0
	s_branch .LBB0_741

; __device__ __forceinline__ unsigned xb_ld(unsigned* p)              { return __hip_atomic_load(p, __ATOMIC_RELAXED, __HIP_MEMORY_SCOPE_AGENT); }
; __device__ __forceinline__ unsigned xb_add(unsigned* p, unsigned v) { return __hip_atomic_fetch_add(p, v, __ATOMIC_RELAXED, __HIP_MEMORY_SCOPE_AGENT); }
; #define XB_SPIN(cond, bar) do { unsigned _sp = 0; while (cond) { __builtin_amdgcn_s_sleep(1); \
;     if ((++_sp & 255u) == 0u) { if (xb_ld(&(bar)[XB_TMO])) break; if (_sp > XB_SPIN_CAP) { atomicAdd(&(bar)[XB_TMO], 1u); break; } } } } while (0)
; __device__ __forceinline__ void xcd_barrier(const XcdBarrier& b) {
;     ...
;             const unsigned tg = og / nx;
;             if (og + 1u == (tg + 1u) * nx) xb_add(&bar[XB_TOPGEN], 1u);
;             else XB_SPIN(xb_ld(&bar[XB_TOPGEN]) == tg, bar);
;             __builtin_amdgcn_fence(__ATOMIC_ACQUIRE, "agent");
;             xb_add(&bar[XB_XGEN(b.x)], 1u);
;             asm volatile("s_waitcnt vmcnt(0)" ::: "memory");
.LBB0_768:
	s_or_b64 exec, exec, s[8:9]
	s_mov_b64 s[8:9], exec
	v_mbcnt_lo_u32_b32 v1, s8, 0
	v_mbcnt_hi_u32_b32 v1, s9, v1
	v_cmp_eq_u32_e32 vcc, 0, v1
	s_waitcnt vmcnt(0)
	buffer_inv sc1
	s_and_saveexec_b64 s[12:13], vcc
	s_cbranch_execz .LBB0_770
	s_bcnt1_i32_b64 s8, s[8:9]
	v_mov_b32_e32 v1, 0x2000
	v_mov_b32_e32 v2, s8
.LBB0_770:
	s_or_b64 exec, exec, s[12:13]
	s_waitcnt vmcnt(0)

; __device__ __forceinline__ unsigned xb_ld(unsigned* p)              { return __hip_atomic_load(p, __ATOMIC_RELAXED, __HIP_MEMORY_SCOPE_AGENT); }
; __device__ __forceinline__ unsigned xb_add(unsigned* p, unsigned v) { return __hip_atomic_fetch_add(p, v, __ATOMIC_RELAXED, __HIP_MEMORY_SCOPE_AGENT); }
; #define XB_SPIN(cond, bar) do { unsigned _sp = 0; while (cond) { __builtin_amdgcn_s_sleep(1); \
;     if ((++_sp & 255u) == 0u) { if (xb_ld(&(bar)[XB_TMO])) break; if (_sp > XB_SPIN_CAP) { atomicAdd(&(bar)[XB_TMO], 1u); break; } } } } while (0)
; __device__ __forceinline__ void xcd_barrier(const XcdBarrier& b) {
;     ...
;         const unsigned old = xb_add(&bar[XB_XSUB(b.x)], 1u);
;         const unsigned gen = old / nloc;
;         if (old + 1u == (gen + 1u) * nloc) {
;             __builtin_amdgcn_fence(__ATOMIC_RELEASE, "agent");
;             asm volatile("s_waitcnt vmcnt(0)" ::: "memory");
;             const unsigned og = xb_add(&bar[XB_TOP], 1u);
;             const unsigned tg = og / nx;
;             if (og + 1u == (tg + 1u) * nx) xb_add(&bar[XB_TOPGEN], 1u);
;             else XB_SPIN(xb_ld(&bar[XB_TOPGEN]) == tg, bar);
;             __builtin_amdgcn_fence(__ATOMIC_ACQUIRE, "agent");
;             xb_add(&bar[XB_XGEN(b.x)], 1u);
;             asm volatile("s_waitcnt vmcnt(0)" ::: "memory");
;         } else {
;             XB_SPIN(xb_ld(&bar[XB_XGEN(b.x)]) == gen, bar);
;             __builtin_amdgcn_fence(__ATOMIC_ACQUIRE, "agent");
;             asm volatile("s_waitcnt vmcnt(0)" ::: "memory");
.LBB0_820:
	s_or_b64 exec, exec, s[8:9]
	v_cvt_f32_u32_e32 v5, v3
	s_waitcnt vmcnt(0)
	v_readfirstlane_b32 s6, v4
	v_sub_u32_e32 v4, 0, v3
	v_rcp_iflag_f32_e32 v5, v5
	v_add_u32_e32 v6, s6, v2
	v_mul_f32_e32 v5, 0x4f7ffffe, v5
	v_cvt_u32_f32_e32 v5, v5
	v_mul_lo_u32 v2, v4, v5
	v_mul_hi_u32 v2, v5, v2
	v_add_u32_e32 v2, v5, v2
	v_mul_hi_u32 v2, v6, v2
	v_mul_lo_u32 v4, v2, v3
	v_sub_u32_e32 v4, v6, v4
	v_add_u32_e32 v5, 1, v2
	v_cmp_ge_u32_e32 vcc, v4, v3
	s_nop 1
	v_cndmask_b32_e32 v2, v2, v5, vcc
	v_sub_u32_e32 v5, v4, v3
	v_cndmask_b32_e32 v4, v4, v5, vcc
	v_add_u32_e32 v5, 1, v2
	v_cmp_ge_u32_e32 vcc, v4, v3
	v_add_u32_e32 v4, 1, v6
	s_nop 0
	v_cndmask_b32_e32 v2, v2, v5, vcc
	v_mul_lo_u32 v5, v3, v2
	v_add_u32_e32 v3, v5, v3
	v_cmp_ne_u32_e32 vcc, v4, v3
	s_and_saveexec_b64 s[6:7], vcc
	s_xor_b64 s[6:7], exec, s[6:7]
	s_cbranch_execz .LBB0_834
	s_waitcnt lgkmcnt(0)
	v_mov_b32_e32 v1, 0x3500
	global_load_dword v1, v1, s[30:31] sc1
	s_add_u32 s10, s30, 0x3500
	s_addc_u32 s11, s31, 0
	s_waitcnt vmcnt(0)
	v_cmp_eq_u32_e32 vcc, v1, v2
	s_and_saveexec_b64 s[8:9], vcc
	s_cbranch_execz .LBB0_833
	s_mov_b32 s24, 1
	s_mov_b64 s[12:13], 0
	v_mov_b32_e32 v1, 0
	s_branch .LBB0_824

; __device__ __forceinline__ unsigned xb_ld(unsigned* p)              { return __hip_atomic_load(p, __ATOMIC_RELAXED, __HIP_MEMORY_SCOPE_AGENT); }
; __device__ __forceinline__ unsigned xb_add(unsigned* p, unsigned v) { return __hip_atomic_fetch_add(p, v, __ATOMIC_RELAXED, __HIP_MEMORY_SCOPE_AGENT); }
; #define XB_SPIN(cond, bar) do { unsigned _sp = 0; while (cond) { __builtin_amdgcn_s_sleep(1); \
;     if ((++_sp & 255u) == 0u) { if (xb_ld(&(bar)[XB_TMO])) break; if (_sp > XB_SPIN_CAP) { atomicAdd(&(bar)[XB_TMO], 1u); break; } } } } while (0)
; __device__ __forceinline__ void xcd_barrier(const XcdBarrier& b) {
;     ...
;             const unsigned tg = og / nx;
;             if (og + 1u == (tg + 1u) * nx) xb_add(&bar[XB_TOPGEN], 1u);
;             else XB_SPIN(xb_ld(&bar[XB_TOPGEN]) == tg, bar);
;             __builtin_amdgcn_fence(__ATOMIC_ACQUIRE, "agent");
;             xb_add(&bar[XB_XGEN(b.x)], 1u);
;             asm volatile("s_waitcnt vmcnt(0)" ::: "memory");
.LBB0_851:
	s_or_b64 exec, exec, s[8:9]
	s_mov_b64 s[8:9], exec
	v_mbcnt_lo_u32_b32 v1, s8, 0
	v_mbcnt_hi_u32_b32 v1, s9, v1
	v_cmp_eq_u32_e32 vcc, 0, v1
	s_waitcnt vmcnt(0)
	buffer_inv sc1
	s_and_saveexec_b64 s[10:11], vcc
	s_cbranch_execz .LBB0_853
	s_bcnt1_i32_b64 s8, s[8:9]
	v_mov_b32_e32 v1, 0x2000
	v_mov_b32_e32 v2, s8
.LBB0_853:
	s_or_b64 exec, exec, s[10:11]
	s_waitcnt vmcnt(0)

; __device__ __forceinline__ unsigned xb_ld(unsigned* p)              { return __hip_atomic_load(p, __ATOMIC_RELAXED, __HIP_MEMORY_SCOPE_AGENT); }
; __device__ __forceinline__ unsigned xb_add(unsigned* p, unsigned v) { return __hip_atomic_fetch_add(p, v, __ATOMIC_RELAXED, __HIP_MEMORY_SCOPE_AGENT); }
; #define XB_SPIN(cond, bar) do { unsigned _sp = 0; while (cond) { __builtin_amdgcn_s_sleep(1); \
;     if ((++_sp & 255u) == 0u) { if (xb_ld(&(bar)[XB_TMO])) break; if (_sp > XB_SPIN_CAP) { atomicAdd(&(bar)[XB_TMO], 1u); break; } } } } while (0)
; __device__ __forceinline__ void xcd_barrier(const XcdBarrier& b) {
;     ...
;         const unsigned old = xb_add(&bar[XB_XSUB(b.x)], 1u);
;         const unsigned gen = old / nloc;
;         if (old + 1u == (gen + 1u) * nloc) {
;             __builtin_amdgcn_fence(__ATOMIC_RELEASE, "agent");
;             asm volatile("s_waitcnt vmcnt(0)" ::: "memory");
;             const unsigned og = xb_add(&bar[XB_TOP], 1u);
;             const unsigned tg = og / nx;
;             if (og + 1u == (tg + 1u) * nx) xb_add(&bar[XB_TOPGEN], 1u);
;             else XB_SPIN(xb_ld(&bar[XB_TOPGEN]) == tg, bar);
;             __builtin_amdgcn_fence(__ATOMIC_ACQUIRE, "agent");
;             xb_add(&bar[XB_XGEN(b.x)], 1u);
;             asm volatile("s_waitcnt vmcnt(0)" ::: "memory");
;         } else {
;             XB_SPIN(xb_ld(&bar[XB_XGEN(b.x)]) == gen, bar);
;             __builtin_amdgcn_fence(__ATOMIC_ACQUIRE, "agent");
;             asm volatile("s_waitcnt vmcnt(0)" ::: "memory");
.LBB0_913:
	s_or_b64 exec, exec, s[14:15]
	v_cvt_f32_u32_e32 v5, v3
	s_waitcnt vmcnt(0)
	v_readfirstlane_b32 s8, v4
	v_sub_u32_e32 v4, 0, v3
	v_rcp_iflag_f32_e32 v5, v5
	v_add_u32_e32 v6, s8, v2
	v_mul_f32_e32 v5, 0x4f7ffffe, v5
	v_cvt_u32_f32_e32 v5, v5
	v_mul_lo_u32 v2, v4, v5
	v_mul_hi_u32 v2, v5, v2
	v_add_u32_e32 v2, v5, v2
	v_mul_hi_u32 v2, v6, v2
	v_mul_lo_u32 v4, v2, v3
	v_sub_u32_e32 v4, v6, v4
	v_add_u32_e32 v5, 1, v2
	v_cmp_ge_u32_e32 vcc, v4, v3
	s_nop 1
	v_cndmask_b32_e32 v2, v2, v5, vcc
	v_sub_u32_e32 v5, v4, v3
	v_cndmask_b32_e32 v4, v4, v5, vcc
	v_add_u32_e32 v5, 1, v2
	v_cmp_ge_u32_e32 vcc, v4, v3
	v_add_u32_e32 v4, 1, v6
	s_nop 0
	v_cndmask_b32_e32 v2, v2, v5, vcc
	v_mul_lo_u32 v5, v3, v2
	v_add_u32_e32 v3, v5, v3
	v_cmp_ne_u32_e32 vcc, v4, v3
	s_and_saveexec_b64 s[8:9], vcc
	s_xor_b64 s[8:9], exec, s[8:9]
	s_cbranch_execz .LBB0_927
	s_waitcnt lgkmcnt(0)
	v_mov_b32_e32 v1, 0x3500
	global_load_dword v1, v1, s[30:31] sc1
	s_add_u32 s16, s30, 0x3500
	s_addc_u32 s17, s31, 0
	s_waitcnt vmcnt(0)
	v_cmp_eq_u32_e32 vcc, v1, v2
	s_and_saveexec_b64 s[14:15], vcc
	s_cbranch_execz .LBB0_926
	s_mov_b32 s33, 1
	s_mov_b64 s[20:21], 0
	v_mov_b32_e32 v1, 0
	s_branch .LBB0_917

; __device__ __forceinline__ unsigned xb_ld(unsigned* p)              { return __hip_atomic_load(p, __ATOMIC_RELAXED, __HIP_MEMORY_SCOPE_AGENT); }
; __device__ __forceinline__ unsigned xb_add(unsigned* p, unsigned v) { return __hip_atomic_fetch_add(p, v, __ATOMIC_RELAXED, __HIP_MEMORY_SCOPE_AGENT); }
; #define XB_SPIN(cond, bar) do { unsigned _sp = 0; while (cond) { __builtin_amdgcn_s_sleep(1); \
;     if ((++_sp & 255u) == 0u) { if (xb_ld(&(bar)[XB_TMO])) break; if (_sp > XB_SPIN_CAP) { atomicAdd(&(bar)[XB_TMO], 1u); break; } } } } while (0)
; __device__ __forceinline__ void xcd_barrier(const XcdBarrier& b) {
;     ...
;             const unsigned tg = og / nx;
;             if (og + 1u == (tg + 1u) * nx) xb_add(&bar[XB_TOPGEN], 1u);
;             else XB_SPIN(xb_ld(&bar[XB_TOPGEN]) == tg, bar);
;             __builtin_amdgcn_fence(__ATOMIC_ACQUIRE, "agent");
;             xb_add(&bar[XB_XGEN(b.x)], 1u);
;             asm volatile("s_waitcnt vmcnt(0)" ::: "memory");
.LBB0_944:
	s_or_b64 exec, exec, s[14:15]
	s_mov_b64 s[14:15], exec
	v_mbcnt_lo_u32_b32 v1, s14, 0
	v_mbcnt_hi_u32_b32 v1, s15, v1
	v_cmp_eq_u32_e32 vcc, 0, v1
	s_waitcnt vmcnt(0)
	buffer_inv sc1
	s_and_saveexec_b64 s[16:17], vcc
	s_cbranch_execz .LBB0_946
	s_bcnt1_i32_b64 s14, s[14:15]
	v_mov_b32_e32 v1, 0x2000
	v_mov_b32_e32 v2, s14
.LBB0_946:
	s_or_b64 exec, exec, s[16:17]
	s_waitcnt vmcnt(0)

; __device__ __forceinline__ unsigned xb_ld(unsigned* p)              { return __hip_atomic_load(p, __ATOMIC_RELAXED, __HIP_MEMORY_SCOPE_AGENT); }
; __device__ __forceinline__ unsigned xb_add(unsigned* p, unsigned v) { return __hip_atomic_fetch_add(p, v, __ATOMIC_RELAXED, __HIP_MEMORY_SCOPE_AGENT); }
; #define XB_SPIN(cond, bar) do { unsigned _sp = 0; while (cond) { __builtin_amdgcn_s_sleep(1); \
;     if ((++_sp & 255u) == 0u) { if (xb_ld(&(bar)[XB_TMO])) break; if (_sp > XB_SPIN_CAP) { atomicAdd(&(bar)[XB_TMO], 1u); break; } } } } while (0)
; __device__ __forceinline__ void xcd_barrier(const XcdBarrier& b) {
;     ...
;             const unsigned tg = og / nx;
;             if (og + 1u == (tg + 1u) * nx) xb_add(&bar[XB_TOPGEN], 1u);
;             else XB_SPIN(xb_ld(&bar[XB_TOPGEN]) == tg, bar);
;             __builtin_amdgcn_fence(__ATOMIC_ACQUIRE, "agent");
;             xb_add(&bar[XB_XGEN(b.x)], 1u);
;             asm volatile("s_waitcnt vmcnt(0)" ::: "memory");
.LBB0_1035:
	s_or_b64 exec, exec, s[14:15]
	s_mov_b64 s[14:15], exec
	v_mbcnt_lo_u32_b32 v1, s14, 0
	v_mbcnt_hi_u32_b32 v1, s15, v1
	v_cmp_eq_u32_e32 vcc, 0, v1
	s_waitcnt vmcnt(0)
	buffer_inv sc1
	s_and_saveexec_b64 s[16:17], vcc
	s_cbranch_execz .LBB0_1037
	s_bcnt1_i32_b64 s14, s[14:15]
	v_mov_b32_e32 v1, 0x2000
	v_mov_b32_e32 v2, s14
.LBB0_1037:
	s_or_b64 exec, exec, s[16:17]
	s_waitcnt vmcnt(0)

; __device__ __forceinline__ unsigned xb_ld(unsigned* p)              { return __hip_atomic_load(p, __ATOMIC_RELAXED, __HIP_MEMORY_SCOPE_AGENT); }
; __device__ __forceinline__ unsigned xb_add(unsigned* p, unsigned v) { return __hip_atomic_fetch_add(p, v, __ATOMIC_RELAXED, __HIP_MEMORY_SCOPE_AGENT); }
; #define XB_SPIN(cond, bar) do { unsigned _sp = 0; while (cond) { __builtin_amdgcn_s_sleep(1); \
;     if ((++_sp & 255u) == 0u) { if (xb_ld(&(bar)[XB_TMO])) break; if (_sp > XB_SPIN_CAP) { atomicAdd(&(bar)[XB_TMO], 1u); break; } } } } while (0)
; __device__ __forceinline__ void xcd_barrier(const XcdBarrier& b) {
;     ...
;             const unsigned tg = og / nx;
;             if (og + 1u == (tg + 1u) * nx) xb_add(&bar[XB_TOPGEN], 1u);
;             else XB_SPIN(xb_ld(&bar[XB_TOPGEN]) == tg, bar);
;             __builtin_amdgcn_fence(__ATOMIC_ACQUIRE, "agent");
;             xb_add(&bar[XB_XGEN(b.x)], 1u);
;             asm volatile("s_waitcnt vmcnt(0)" ::: "memory");
.LBB0_1104:
	s_or_b64 exec, exec, s[14:15]
	s_mov_b64 s[14:15], exec
	v_mbcnt_lo_u32_b32 v1, s14, 0
	v_mbcnt_hi_u32_b32 v1, s15, v1
	v_cmp_eq_u32_e32 vcc, 0, v1
	s_waitcnt vmcnt(0)
	buffer_inv sc1
	s_and_saveexec_b64 s[16:17], vcc
	s_cbranch_execz .LBB0_1106
	s_bcnt1_i32_b64 s14, s[14:15]
	v_mov_b32_e32 v1, 0x2000
	v_mov_b32_e32 v2, s14
.LBB0_1106:
	s_or_b64 exec, exec, s[16:17]
	s_waitcnt vmcnt(0)

; __device__ __forceinline__ unsigned xb_ld(unsigned* p)              { return __hip_atomic_load(p, __ATOMIC_RELAXED, __HIP_MEMORY_SCOPE_AGENT); }
; __device__ __forceinline__ unsigned xb_add(unsigned* p, unsigned v) { return __hip_atomic_fetch_add(p, v, __ATOMIC_RELAXED, __HIP_MEMORY_SCOPE_AGENT); }
; #define XB_SPIN(cond, bar) do { unsigned _sp = 0; while (cond) { __builtin_amdgcn_s_sleep(1); \
;     if ((++_sp & 255u) == 0u) { if (xb_ld(&(bar)[XB_TMO])) break; if (_sp > XB_SPIN_CAP) { atomicAdd(&(bar)[XB_TMO], 1u); break; } } } } while (0)
; __device__ __forceinline__ void xcd_barrier(const XcdBarrier& b) {
;     ...
;         const unsigned old = xb_add(&bar[XB_XSUB(b.x)], 1u);
;         const unsigned gen = old / nloc;
;         if (old + 1u == (gen + 1u) * nloc) {
;             __builtin_amdgcn_fence(__ATOMIC_RELEASE, "agent");
;             asm volatile("s_waitcnt vmcnt(0)" ::: "memory");
;             const unsigned og = xb_add(&bar[XB_TOP], 1u);
;             const unsigned tg = og / nx;
;             if (og + 1u == (tg + 1u) * nx) xb_add(&bar[XB_TOPGEN], 1u);
;             else XB_SPIN(xb_ld(&bar[XB_TOPGEN]) == tg, bar);
;             __builtin_amdgcn_fence(__ATOMIC_ACQUIRE, "agent");
;             xb_add(&bar[XB_XGEN(b.x)], 1u);
;             asm volatile("s_waitcnt vmcnt(0)" ::: "memory");
;         } else {
;             XB_SPIN(xb_ld(&bar[XB_XGEN(b.x)]) == gen, bar);
;             __builtin_amdgcn_fence(__ATOMIC_ACQUIRE, "agent");
;             asm volatile("s_waitcnt vmcnt(0)" ::: "memory");
.LBB0_1168:
	s_or_b64 exec, exec, s[6:7]
	v_cvt_f32_u32_e32 v5, v3
	s_waitcnt vmcnt(0)
	v_readfirstlane_b32 s4, v4
	v_sub_u32_e32 v4, 0, v3
	v_rcp_iflag_f32_e32 v5, v5
	v_add_u32_e32 v6, s4, v2
	v_mul_f32_e32 v5, 0x4f7ffffe, v5
	v_cvt_u32_f32_e32 v5, v5
	v_mul_lo_u32 v2, v4, v5
	v_mul_hi_u32 v2, v5, v2
	v_add_u32_e32 v2, v5, v2
	v_mul_hi_u32 v2, v6, v2
	v_mul_lo_u32 v4, v2, v3
	v_sub_u32_e32 v4, v6, v4
	v_add_u32_e32 v5, 1, v2
	v_cmp_ge_u32_e32 vcc, v4, v3
	s_nop 1
	v_cndmask_b32_e32 v2, v2, v5, vcc
	v_sub_u32_e32 v5, v4, v3
	v_cndmask_b32_e32 v4, v4, v5, vcc
	v_add_u32_e32 v5, 1, v2
	v_cmp_ge_u32_e32 vcc, v4, v3
	v_add_u32_e32 v4, 1, v6
	s_nop 0
	v_cndmask_b32_e32 v2, v2, v5, vcc
	v_mul_lo_u32 v5, v3, v2
	v_add_u32_e32 v3, v5, v3
	v_cmp_ne_u32_e32 vcc, v4, v3
	s_and_saveexec_b64 s[4:5], vcc
	s_xor_b64 s[4:5], exec, s[4:5]
	s_cbranch_execz .LBB0_1182
	s_waitcnt lgkmcnt(0)
	v_mov_b32_e32 v1, 0x3500
	global_load_dword v1, v1, s[30:31] sc1
	s_add_u32 s8, s30, 0x3500
	s_addc_u32 s9, s31, 0
	s_waitcnt vmcnt(0)
	v_cmp_eq_u32_e32 vcc, v1, v2
	s_and_saveexec_b64 s[6:7], vcc
	s_cbranch_execz .LBB0_1181
	s_mov_b32 s20, 1
	s_mov_b64 s[10:11], 0
	v_mov_b32_e32 v1, 0
	s_branch .LBB0_1172

; __device__ __forceinline__ unsigned xb_ld(unsigned* p)              { return __hip_atomic_load(p, __ATOMIC_RELAXED, __HIP_MEMORY_SCOPE_AGENT); }
; __device__ __forceinline__ unsigned xb_add(unsigned* p, unsigned v) { return __hip_atomic_fetch_add(p, v, __ATOMIC_RELAXED, __HIP_MEMORY_SCOPE_AGENT); }
; #define XB_SPIN(cond, bar) do { unsigned _sp = 0; while (cond) { __builtin_amdgcn_s_sleep(1); \
;     if ((++_sp & 255u) == 0u) { if (xb_ld(&(bar)[XB_TMO])) break; if (_sp > XB_SPIN_CAP) { atomicAdd(&(bar)[XB_TMO], 1u); break; } } } } while (0)
; __device__ __forceinline__ void xcd_barrier(const XcdBarrier& b) {
;     ...
;             const unsigned tg = og / nx;
;             if (og + 1u == (tg + 1u) * nx) xb_add(&bar[XB_TOPGEN], 1u);
;             else XB_SPIN(xb_ld(&bar[XB_TOPGEN]) == tg, bar);
;             __builtin_amdgcn_fence(__ATOMIC_ACQUIRE, "agent");
;             xb_add(&bar[XB_XGEN(b.x)], 1u);
;             asm volatile("s_waitcnt vmcnt(0)" ::: "memory");
.LBB0_1199:
	s_or_b64 exec, exec, s[6:7]
	s_mov_b64 s[6:7], exec
	v_mbcnt_lo_u32_b32 v1, s6, 0
	v_mbcnt_hi_u32_b32 v1, s7, v1
	v_cmp_eq_u32_e32 vcc, 0, v1
	s_waitcnt vmcnt(0)
	buffer_inv sc1
	s_and_saveexec_b64 s[8:9], vcc
	s_cbranch_execz .LBB0_1201
	s_bcnt1_i32_b64 s6, s[6:7]
	v_mov_b32_e32 v1, 0x2000
	v_mov_b32_e32 v2, s6
.LBB0_1201:
	s_or_b64 exec, exec, s[8:9]
	s_waitcnt vmcnt(0)
